# device-wide barrier: the XCD leader bumps its XCD's release word before its own cache invalidate (invalidate no longer delays the other workgroups' release)
# baseline (speedup 1.0000x reference)
; __device__ __forceinline__ unsigned xb_add(unsigned* p, unsigned v) { return __hip_atomic_fetch_add(p, v, __ATOMIC_RELAXED, __HIP_MEMORY_SCOPE_AGENT); }
; __device__ __forceinline__ void xcd_barrier(const XcdBarrier& b) {
;     ...
;             __builtin_amdgcn_fence(__ATOMIC_ACQUIRE, "agent");
;             xb_add(&bar[XB_XGEN(b.x)], 1u);
;             asm volatile("s_waitcnt vmcnt(0)" ::: "memory");
.LBB0_123:
	s_or_b64 exec, exec, s[6:7]
	s_mov_b64 s[6:7], exec
	v_mbcnt_lo_u32_b32 v0, s6, 0
	v_mbcnt_hi_u32_b32 v0, s7, v0
	v_cmp_eq_u32_e32 vcc, 0, v0
	s_waitcnt vmcnt(0)
	s_and_saveexec_b64 s[8:9], vcc
	s_cbranch_execz .LBB0_125
	s_bcnt1_i32_b64 s6, s[6:7]
	v_mov_b32_e32 v0, 0x2000
	v_mov_b32_e32 v1, s6
	global_atomic_add v0, v1, s[4:5] offset:1024
.LBB0_125:
	s_or_b64 exec, exec, s[8:9]
	buffer_inv sc1
	s_waitcnt vmcnt(0)

; __device__ __forceinline__ unsigned xb_add(unsigned* p, unsigned v) { return __hip_atomic_fetch_add(p, v, __ATOMIC_RELAXED, __HIP_MEMORY_SCOPE_AGENT); }
; __device__ __forceinline__ void xcd_barrier(const XcdBarrier& b) {
;     ...
;             __builtin_amdgcn_fence(__ATOMIC_ACQUIRE, "agent");
;             xb_add(&bar[XB_XGEN(b.x)], 1u);
;             asm volatile("s_waitcnt vmcnt(0)" ::: "memory");
.LBB0_580:
	s_or_b64 exec, exec, s[8:9]
	s_mov_b64 s[8:9], exec
	v_mbcnt_lo_u32_b32 v0, s8, 0
	v_mbcnt_hi_u32_b32 v0, s9, v0
	v_cmp_eq_u32_e32 vcc, 0, v0
	s_waitcnt vmcnt(0)
	s_and_saveexec_b64 s[12:13], vcc
	s_cbranch_execz .LBB0_582
	s_bcnt1_i32_b64 s8, s[8:9]
	v_mov_b32_e32 v0, 0x2000
	v_mov_b32_e32 v1, s8
	global_atomic_add v0, v1, s[4:5] offset:1024
.LBB0_582:
	s_or_b64 exec, exec, s[12:13]
	buffer_inv sc1
	s_waitcnt vmcnt(0)

; __device__ __forceinline__ unsigned xb_add(unsigned* p, unsigned v) { return __hip_atomic_fetch_add(p, v, __ATOMIC_RELAXED, __HIP_MEMORY_SCOPE_AGENT); }
; __device__ __forceinline__ void xcd_barrier(const XcdBarrier& b) {
;     ...
;             __builtin_amdgcn_fence(__ATOMIC_ACQUIRE, "agent");
;             xb_add(&bar[XB_XGEN(b.x)], 1u);
;             asm volatile("s_waitcnt vmcnt(0)" ::: "memory");
.LBB0_985:
	s_or_b64 exec, exec, s[4:5]
	s_mov_b64 s[4:5], exec
	v_mbcnt_lo_u32_b32 v0, s4, 0
	v_mbcnt_hi_u32_b32 v0, s5, v0
	v_cmp_eq_u32_e32 vcc, 0, v0
	s_waitcnt vmcnt(0)
	s_and_saveexec_b64 s[6:7], vcc
	s_cbranch_execz .LBB0_987
	s_bcnt1_i32_b64 s4, s[4:5]
	v_mov_b32_e32 v0, 0x2000
	v_mov_b32_e32 v1, s4
	global_atomic_add v0, v1, s[2:3] offset:1024
.LBB0_987:
	s_or_b64 exec, exec, s[6:7]
	buffer_inv sc1
	s_waitcnt vmcnt(0)
